# v077 + in-projection unit order (layer 1): three-unit workgroups take the q,k,v column tiles, two-unit workgroups the gelu tiles
# baseline (speedup 1.0000x reference)
.LBB0_221:
.LBB0_222:
	s_or_b64 exec, exec, s[10:11]
	v_mov_b32_e32 v12, v0
	v_cndmask_b32_e64 v2, 0, 1, s[14:15]
	s_waitcnt lgkmcnt(0)
	s_barrier
	v_cmp_ne_u32_e64 s[10:11], 1, v2
	s_andn2_b64 vcc, exec, s[14:15]
	v_readfirstlane_b32 s6, v12
	s_cbranch_vccnz .LBB0_224
	s_ashr_i32 s4, s54, 31
	s_lshr_b32 s4, s4, 29
	s_add_i32 s4, s54, s4
	s_ashr_i32 s9, s4, 3
	s_and_b32 s4, s4, -8
	s_sub_i32 s4, s54, s4
	s_cmp_lt_i32 s4, 0
	s_movk_i32 s14, 0x51
	s_cselect_b32 s14, s14, 0x50
	s_mul_i32 s4, s4, s14
	s_add_i32 s4, s4, s9
	s_mul_hi_i32 s9, s4, 0x66666667
	s_lshr_b32 s14, s9, 31
	s_ashr_i32 s9, s9, 5
	s_add_i32 s9, s9, s14
	s_lshl_b32 s14, s9, 3
	s_mulk_i32 s9, 0x50
	s_sub_i32 s4, s4, s9
	s_bfe_i32 s9, s4, 0x80000
	s_bfe_u32 s9, s9, 0x3000c
	s_add_i32 s9, s4, s9
	s_bfe_i32 s15, s9, 0x80000
	s_and_b32 s9, s9, 0xf8
	s_sub_i32 s4, s4, s9
	s_sext_i32_i16 s15, s15
	s_sext_i32_i8 s4, s4
	s_add_i32 s16, s14, s4
	s_ashr_i32 s14, s15, 3
	s_cmp_eq_u32 s5, 0
	s_cselect_b32 s99, 0, 1
	s_lshr_b32 s98, s14, 2
	s_lshl_b32 s98, s98, 1
	s_bitcmp1_b32 s14, 0
	s_addc_u32 s98, s98, 0
	s_add_i32 s100, s98, 6
	s_bitcmp1_b32 s14, 1
	s_cselect_b32 s98, s100, s98
	s_cmp_lg_u32 s99, 0
	s_cselect_b32 s14, s98, s14

.LBB0_230:
	s_add_i32 s80, s80, 1
	s_mul_i32 s6, s80, s89
	s_mul_hi_u32 s12, s80, s8
	s_add_i32 s12, s12, s6
	s_mul_i32 s6, s80, s8
	s_add_u32 s72, s6, s54
	s_addc_u32 s73, s12, s55
	v_mov_b64_e32 v[4:5], 0x280
	v_cmp_lt_i64_e64 s[12:13], s[72:73], v[4:5]
	v_mov_b64_e32 v[4:5], 0x27f
	v_cmp_gt_i64_e32 vcc, s[72:73], v[4:5]
	s_cbranch_vccnz .LBB0_232
	s_ashr_i32 s6, s72, 31
	s_lshr_b32 s6, s6, 29
	s_add_i32 s6, s72, s6
	s_ashr_i32 s15, s6, 3
	s_and_b32 s6, s6, -8
	s_sub_i32 s6, s72, s6
	s_cmp_lt_i32 s6, 0
	s_movk_i32 s17, 0x51
	s_cselect_b32 s17, s17, 0x50
	s_mul_i32 s6, s6, s17
	s_add_i32 s6, s6, s15
	s_mul_hi_i32 s15, s6, 0x66666667
	s_lshr_b32 s17, s15, 31
	s_ashr_i32 s15, s15, 5
	s_add_i32 s15, s15, s17
	s_lshl_b32 s17, s15, 3
	s_sub_i32 s24, 64, s17
	s_min_i32 s24, s24, 8
	s_abs_i32 s33, s24
	v_cvt_f32_u32_e32 v4, s33
	s_sub_i32 s69, 0, s33
	s_mulk_i32 s15, 0x50
	s_sub_i32 s6, s6, s15
	v_rcp_iflag_f32_e32 v4, v4
	s_abs_i32 s15, s6
	s_xor_b32 s68, s6, s24
	s_ashr_i32 s68, s68, 31
	v_mul_f32_e32 v4, 0x4f7ffffe, v4
	v_cvt_u32_f32_e32 v4, v4
	s_nop 0
	v_readfirstlane_b32 s70, v4
	s_mul_i32 s69, s69, s70
	s_mul_hi_u32 s69, s70, s69
	s_add_i32 s70, s70, s69
	s_mul_hi_u32 s69, s15, s70
	s_mul_i32 s70, s69, s33
	s_sub_i32 s15, s15, s70
	s_add_i32 s71, s69, 1
	s_sub_i32 s70, s15, s33
	s_cmp_ge_u32 s15, s33
	s_cselect_b32 s69, s71, s69
	s_cselect_b32 s15, s70, s15
	s_add_i32 s70, s69, 1
	s_cmp_ge_u32 s15, s33
	s_cselect_b32 s15, s70, s69
	s_xor_b32 s15, s15, s68
	s_sub_i32 s68, s15, s68
	s_mul_i32 s15, s68, s24
	s_sub_i32 s6, s6, s15
	s_add_i32 s70, s17, s6
	s_cmp_eq_u32 s5, 0
	s_cselect_b32 s99, 0, 1
	s_lshr_b32 s98, s68, 2
	s_lshl_b32 s98, s98, 1
	s_bitcmp1_b32 s68, 0
	s_addc_u32 s98, s98, 0
	s_add_i32 s100, s98, 6
	s_bitcmp1_b32 s68, 1
	s_cselect_b32 s98, s100, s98
	s_cmp_lg_u32 s99, 0
	s_cselect_b32 s68, s98, s68
